# v33 + merge loop two iterations per trip (14 loads in flight) now that the merge sits on the 128 merge-doing workgroups' path
# baseline (speedup 1.0000x reference)
; #define MRG(F) o.F = pk_bf16((w0 * bflo(a.F) + w1 * bflo(bq.F) + w2 * bflo(cq.F)) * bflo(gq.F), (w0 * bfhi(a.F) + w1 * bfhi(bq.F) + w2 * bfhi(cq.F)) * bfhi(gq.F))
; __device__ __forceinline__ void merge_phase(u16* OG, const float* LSE, const u16* AG, int bid, int nb) {
;     for (int idx = bid * 512 + threadIdx.x; idx < TT * 64; idx += nb * 512) {
;         const int tok = idx >> 6, h = (idx >> 3) & 7, ch = idx & 7; const size_t off = (size_t)tok * 512 + h * 64 + 8 * ch;
;         const float l0 = LSE[(size_t)tok * 8 + h], l1 = LSE[(size_t)TT * 8 + (size_t)tok * 8 + h], l2 = LSE[(size_t)2 * TT * 8 + (size_t)tok * 8 + h];
;         const float m = fmaxf(l0, fmaxf(l1, l2)); float w0 = __builtin_amdgcn_exp2f(l0 - m), w1 = __builtin_amdgcn_exp2f(l1 - m), w2 = __builtin_amdgcn_exp2f(l2 - m);
;         const float inv = 1.0f / (w0 + w1 + w2); w0 *= inv; w1 *= inv; w2 *= inv;
;         const u32x4 a = *(const u32x4*)(OG + off), bq = *(const u32x4*)(OG + (size_t)TT * 512 + off), cq = *(const u32x4*)(OG + (size_t)2 * TT * 512 + off), gq = *(const u32x4*)(AG + off);
;         u32x4 o;
;     ...
;         MRG(x); MRG(y); MRG(z); MRG(w);
.Ls3d_rel:
.Ls3d_skip:
	s_mov_b64 exec, s[6:7]
	s_barrier
	s_add_u32 s4, s76, 0x1000000
	s_addc_u32 s5, s77, 0
	s_lshl_b32 s6, s2, 9
	v_add_u32_e32 v1, s6, v188
	v_add_u32_e32 v0, 0xffff0000, v1
	s_mov_b32 s16, 0x100000
	v_cmp_gt_u32_e32 vcc, s16, v0
	s_and_saveexec_b64 s[6:7], vcc
	s_cbranch_execz .LBB0_450
	s_add_u32 s8, s78, 0x1b00000
	s_addc_u32 s9, s79, 0
	s_add_u32 s10, s76, 0x3000000
	s_addc_u32 s11, s77, 0
	s_add_u32 s12, s76, 0x2000000
	s_addc_u32 s13, s77, 0
	v_add_u32_e32 v2, 0xfffe0000, v1
	v_lshlrev_b32_e32 v3, 3, v0
	s_mov_b64 s[14:15], 0
	v_mov_b32_e32 v1, 0
	s_mov_b32 s17, 0x80000
	s_mov_b32 s18, 0xeffff
	v_mov_b32_e32 v49, 0
.Lmg_top:
	v_readfirstlane_b32 s22, v2
	s_nop 3
	s_add_i32 s24, s22, 0x20000
	s_cmp_gt_i32 s24, 0xfffff
	s_cbranch_scc1 .Lmg_tail
	v_add_u32_e32 v2, 0x10000, v2
	v_ashrrev_i32_e32 v4, 6, v2
	v_ashrrev_i32_e32 v5, 31, v4
	v_bfe_u32 v0, v2, 3, 3
	v_lshlrev_b64 v[6:7], 9, v[4:5]
	v_lshlrev_b64 v[4:5], 5, v[4:5]
	v_lshlrev_b32_e32 v9, 6, v0
	v_lshlrev_b32_e32 v0, 2, v0
	v_lshl_add_u64 v[4:5], s[8:9], 0, v[4:5]
	v_lshl_add_u64 v[20:21], v[4:5], 0, v[0:1]
	v_and_b32_e32 v8, 56, v3
	v_add_co_u32_e32 v22, vcc, s17, v20
	v_or3_b32 v6, v6, v9, v8
	s_nop 0
	v_addc_co_u32_e32 v23, vcc, 0, v21, vcc
	v_lshlrev_b64 v[4:5], 1, v[6:7]
	v_add_co_u32_e32 v24, vcc, s16, v20
	v_lshl_add_u64 v[26:27], s[76:77], 0, v[4:5]
	s_nop 0
	v_addc_co_u32_e32 v25, vcc, 0, v21, vcc
	v_lshl_add_u64 v[28:29], s[4:5], 0, v[4:5]
	v_lshl_add_u64 v[30:31], s[12:13], 0, v[4:5]
	v_lshl_add_u64 v[32:33], s[10:11], 0, v[4:5]
	global_load_dword v0, v[20:21], off sc1
	global_load_dword v40, v[22:23], off sc1
	global_load_dword v41, v[24:25], off sc1
	global_load_dwordx4 v[4:7], v[28:29], off sc1
	global_load_dwordx4 v[8:11], v[26:27], off sc1
	global_load_dwordx4 v[12:15], v[30:31], off sc1
	global_load_dwordx4 v[16:19], v[32:33], off sc1
	v_add_u32_e32 v3, 0x80000, v3
	v_add_u32_e32 v2, 0x10000, v2
	v_ashrrev_i32_e32 v52, 6, v2
	v_ashrrev_i32_e32 v53, 31, v52
	v_bfe_u32 v48, v2, 3, 3
	v_lshlrev_b64 v[54:55], 9, v[52:53]
	v_lshlrev_b64 v[52:53], 5, v[52:53]
	v_lshlrev_b32_e32 v57, 6, v48
	v_lshlrev_b32_e32 v48, 2, v48
	v_lshl_add_u64 v[52:53], s[8:9], 0, v[52:53]
	v_lshl_add_u64 v[68:69], v[52:53], 0, v[48:49]
	v_and_b32_e32 v56, 56, v3
	v_add_co_u32_e32 v70, vcc, s17, v68
	v_or3_b32 v54, v54, v57, v56
	s_nop 0
	v_addc_co_u32_e32 v71, vcc, 0, v69, vcc
	v_lshlrev_b64 v[52:53], 1, v[54:55]
	v_add_co_u32_e32 v72, vcc, s16, v68
	v_lshl_add_u64 v[74:75], s[76:77], 0, v[52:53]
	s_nop 0
	v_addc_co_u32_e32 v73, vcc, 0, v69, vcc
	v_lshl_add_u64 v[76:77], s[4:5], 0, v[52:53]
	v_lshl_add_u64 v[78:79], s[12:13], 0, v[52:53]
	v_lshl_add_u64 v[80:81], s[10:11], 0, v[52:53]
	global_load_dword v48, v[68:69], off sc1
	global_load_dword v88, v[70:71], off sc1
	global_load_dword v89, v[72:73], off sc1
	global_load_dwordx4 v[52:55], v[76:77], off sc1
	global_load_dwordx4 v[56:59], v[74:75], off sc1
	global_load_dwordx4 v[60:63], v[78:79], off sc1
	global_load_dwordx4 v[64:67], v[80:81], off sc1
	v_add_u32_e32 v3, 0x80000, v3
	s_waitcnt vmcnt(11)
	v_max3_f32 v42, v0, v40, v41
	v_sub_f32_e32 v0, v0, v42
	s_waitcnt vmcnt(10)
	v_lshlrev_b32_e32 v20, 16, v4
	s_waitcnt vmcnt(9)
	v_and_b32_e32 v21, 0xffff0000, v8
	s_waitcnt vmcnt(7)
; __device__ __forceinline__ void store16_wt(void* p, u32x4 v) { asm volatile("global_store_dwordx4 %0, %1, off sc1\n\ts_nop 1" :: "v"(p), "v"(v) : "memory"); }
; #define MRG(F) o.F = pk_bf16((w0 * bflo(a.F) + w1 * bflo(bq.F) + w2 * bflo(cq.F)) * bflo(gq.F), (w0 * bfhi(a.F) + w1 * bfhi(bq.F) + w2 * bfhi(cq.F)) * bfhi(gq.F))
; __device__ __forceinline__ void merge_phase(u16* OG, const float* LSE, const u16* AG, int bid, int nb) {
;     ...
;         const int tok = idx >> 6, h = (idx >> 3) & 7, ch = idx & 7; const size_t off = (size_t)tok * 512 + h * 64 + 8 * ch;
;         const float l0 = LSE[(size_t)tok * 8 + h], l1 = LSE[(size_t)TT * 8 + (size_t)tok * 8 + h], l2 = LSE[(size_t)2 * TT * 8 + (size_t)tok * 8 + h];
;         const float m = fmaxf(l0, fmaxf(l1, l2)); float w0 = __builtin_amdgcn_exp2f(l0 - m), w1 = __builtin_amdgcn_exp2f(l1 - m), w2 = __builtin_amdgcn_exp2f(l2 - m);
;         const float inv = 1.0f / (w0 + w1 + w2); w0 *= inv; w1 *= inv; w2 *= inv;
;         const u32x4 a = *(const u32x4*)(OG + off), bq = *(const u32x4*)(OG + (size_t)TT * 512 + off), cq = *(const u32x4*)(OG + (size_t)2 * TT * 512 + off), gq = *(const u32x4*)(AG + off);
;         u32x4 o;
;     ...
;         MRG(x); MRG(y); MRG(z); MRG(w);
;     ...
;         store16_wt(OG + off, o);
;     }
	v_lshlrev_b32_e32 v36, 16, v18
	v_and_b32_e32 v37, 0xffff0000, v18
	v_sub_f32_e32 v18, v40, v42
	v_lshlrev_b32_e32 v22, 16, v8
	v_and_b32_e32 v23, 0xffff0000, v4
	v_lshlrev_b32_e32 v24, 16, v12
	v_and_b32_e32 v25, 0xffff0000, v12
	v_lshlrev_b32_e32 v28, 16, v16
	v_and_b32_e32 v29, 0xffff0000, v16
	v_and_b32_e32 v31, 0xffff0000, v9
	v_lshlrev_b32_e32 v4, 16, v9
	v_lshlrev_b32_e32 v8, 16, v13
	v_and_b32_e32 v9, 0xffff0000, v13
	v_lshlrev_b32_e32 v12, 16, v17
	v_and_b32_e32 v13, 0xffff0000, v17
	v_lshlrev_b32_e32 v16, 16, v6
	v_and_b32_e32 v17, 0xffff0000, v10
	v_lshlrev_b32_e32 v32, 16, v10
	v_and_b32_e32 v33, 0xffff0000, v6
	v_lshlrev_b32_e32 v34, 16, v14
	v_and_b32_e32 v35, 0xffff0000, v14
	v_and_b32_e32 v39, 0xffff0000, v11
	v_lshlrev_b32_e32 v6, 16, v11
	v_lshlrev_b32_e32 v10, 16, v15
	v_and_b32_e32 v11, 0xffff0000, v15
	v_lshlrev_b32_e32 v14, 16, v19
	v_and_b32_e32 v15, 0xffff0000, v19
	v_sub_f32_e32 v40, v41, v42
	v_exp_f32_e32 v19, v0
	v_exp_f32_e32 v18, v18
	v_exp_f32_e32 v40, v40
	v_lshlrev_b32_e32 v30, 16, v5
	v_and_b32_e32 v5, 0xffff0000, v5
	v_add_f32_e32 v0, v19, v18
	v_add_f32_e32 v0, v40, v0
	v_div_scale_f32 v41, s[20:21], v0, v0, 1.0
	v_rcp_f32_e32 v43, v41
	v_div_scale_f32 v42, vcc, 1.0, v0, 1.0
	v_lshlrev_b32_e32 v38, 16, v7
	v_fma_f32 v44, -v41, v43, 1.0
	v_fmac_f32_e32 v43, v44, v43
	v_mul_f32_e32 v44, v42, v43
	v_fma_f32 v45, -v41, v44, v42
	v_fmac_f32_e32 v44, v45, v43
	v_fma_f32 v41, -v41, v44, v42
	v_div_fmas_f32 v41, v41, v43, v44
	v_div_fixup_f32 v0, v41, v0, 1.0
	v_and_b32_e32 v7, 0xffff0000, v7
	v_pk_mul_f32 v[18:19], v[18:19], v[0:1] op_sel_hi:[1,0]
	v_mul_f32_e32 v40, v40, v0
	v_pk_mul_f32 v[22:23], v[18:19], v[22:23] op_sel:[1,0] op_sel_hi:[0,1]
	v_pk_mul_f32 v[4:5], v[18:19], v[4:5] op_sel:[1,0] op_sel_hi:[0,1]
	v_pk_mul_f32 v[32:33], v[18:19], v[32:33] op_sel:[1,0] op_sel_hi:[0,1]
	v_pk_mul_f32 v[6:7], v[18:19], v[6:7] op_sel:[1,0] op_sel_hi:[0,1]
	v_pk_fma_f32 v[20:21], v[18:19], v[20:21], v[22:23]
	v_pk_fma_f32 v[4:5], v[18:19], v[30:31], v[4:5]
	v_pk_fma_f32 v[16:17], v[18:19], v[16:17], v[32:33]
	v_pk_fma_f32 v[6:7], v[18:19], v[38:39], v[6:7]
	v_pk_fma_f32 v[18:19], v[40:41], v[24:25], v[20:21] op_sel_hi:[0,1,1]
	v_pk_fma_f32 v[4:5], v[40:41], v[8:9], v[4:5] op_sel_hi:[0,1,1]
	v_pk_fma_f32 v[8:9], v[40:41], v[34:35], v[16:17] op_sel_hi:[0,1,1]
	v_pk_fma_f32 v[6:7], v[40:41], v[10:11], v[6:7] op_sel_hi:[0,1,1]
	v_pk_mul_f32 v[10:11], v[18:19], v[28:29]
	v_pk_mul_f32 v[12:13], v[4:5], v[12:13]
	v_pk_mul_f32 v[8:9], v[8:9], v[36:37]
	v_pk_mul_f32 v[14:15], v[6:7], v[14:15]
	v_cvt_pk_bf16_f32 v4, v10, v11
	v_cvt_pk_bf16_f32 v5, v12, v13
	v_cvt_pk_bf16_f32 v6, v8, v9
	v_cvt_pk_bf16_f32 v7, v14, v15
	global_store_dwordx4 v[26:27], v[4:7], off sc1
	s_nop 1
	s_waitcnt vmcnt(5)
	v_max3_f32 v90, v48, v88, v89
	v_sub_f32_e32 v48, v48, v90
	s_waitcnt vmcnt(4)
	v_lshlrev_b32_e32 v68, 16, v52
	s_waitcnt vmcnt(3)
	v_and_b32_e32 v69, 0xffff0000, v56
	s_waitcnt vmcnt(1)
	v_lshlrev_b32_e32 v84, 16, v66
	v_and_b32_e32 v85, 0xffff0000, v66
	v_sub_f32_e32 v66, v88, v90
	v_lshlrev_b32_e32 v70, 16, v56
	v_and_b32_e32 v71, 0xffff0000, v52
	v_lshlrev_b32_e32 v72, 16, v60
	v_and_b32_e32 v73, 0xffff0000, v60
	v_lshlrev_b32_e32 v76, 16, v64
	v_and_b32_e32 v77, 0xffff0000, v64
	v_and_b32_e32 v79, 0xffff0000, v57
	v_lshlrev_b32_e32 v52, 16, v57
	v_lshlrev_b32_e32 v56, 16, v61
	v_and_b32_e32 v57, 0xffff0000, v61
	v_lshlrev_b32_e32 v60, 16, v65
	v_and_b32_e32 v61, 0xffff0000, v65
	v_lshlrev_b32_e32 v64, 16, v54
	v_and_b32_e32 v65, 0xffff0000, v58
	v_lshlrev_b32_e32 v80, 16, v58
	v_and_b32_e32 v81, 0xffff0000, v54
	v_lshlrev_b32_e32 v82, 16, v62
	v_and_b32_e32 v83, 0xffff0000, v62
	v_and_b32_e32 v87, 0xffff0000, v59
	v_lshlrev_b32_e32 v54, 16, v59
	v_lshlrev_b32_e32 v58, 16, v63
	v_and_b32_e32 v59, 0xffff0000, v63
	v_lshlrev_b32_e32 v62, 16, v67
	v_and_b32_e32 v63, 0xffff0000, v67
	v_sub_f32_e32 v88, v89, v90
	v_exp_f32_e32 v67, v48
	v_exp_f32_e32 v66, v66
	v_exp_f32_e32 v88, v88
	v_lshlrev_b32_e32 v78, 16, v53
	v_and_b32_e32 v53, 0xffff0000, v53
	v_add_f32_e32 v48, v67, v66
	v_add_f32_e32 v48, v88, v48
	v_div_scale_f32 v89, s[20:21], v48, v48, 1.0
	v_rcp_f32_e32 v91, v89
	v_div_scale_f32 v90, vcc, 1.0, v48, 1.0
	v_lshlrev_b32_e32 v86, 16, v55
	v_fma_f32 v92, -v89, v91, 1.0
	v_fmac_f32_e32 v91, v92, v91
	v_mul_f32_e32 v92, v90, v91
	v_fma_f32 v93, -v89, v92, v90
	v_fmac_f32_e32 v92, v93, v91
	v_fma_f32 v89, -v89, v92, v90
	v_div_fmas_f32 v89, v89, v91, v92
	v_div_fixup_f32 v48, v89, v48, 1.0
	v_and_b32_e32 v55, 0xffff0000, v55
	v_pk_mul_f32 v[66:67], v[66:67], v[48:49] op_sel_hi:[1,0]
	v_mul_f32_e32 v88, v88, v48
	v_pk_mul_f32 v[70:71], v[66:67], v[70:71] op_sel:[1,0] op_sel_hi:[0,1]
	v_pk_mul_f32 v[52:53], v[66:67], v[52:53] op_sel:[1,0] op_sel_hi:[0,1]
	v_pk_mul_f32 v[80:81], v[66:67], v[80:81] op_sel:[1,0] op_sel_hi:[0,1]
	v_pk_mul_f32 v[54:55], v[66:67], v[54:55] op_sel:[1,0] op_sel_hi:[0,1]
	v_pk_fma_f32 v[68:69], v[66:67], v[68:69], v[70:71]
	v_pk_fma_f32 v[52:53], v[66:67], v[78:79], v[52:53]
	v_pk_fma_f32 v[64:65], v[66:67], v[64:65], v[80:81]
	v_pk_fma_f32 v[54:55], v[66:67], v[86:87], v[54:55]
	v_pk_fma_f32 v[66:67], v[88:89], v[72:73], v[68:69] op_sel_hi:[0,1,1]
	v_pk_fma_f32 v[52:53], v[88:89], v[56:57], v[52:53] op_sel_hi:[0,1,1]
	v_pk_fma_f32 v[56:57], v[88:89], v[82:83], v[64:65] op_sel_hi:[0,1,1]
	v_pk_fma_f32 v[54:55], v[88:89], v[58:59], v[54:55] op_sel_hi:[0,1,1]
	v_pk_mul_f32 v[58:59], v[66:67], v[76:77]
	v_pk_mul_f32 v[60:61], v[52:53], v[60:61]
	v_pk_mul_f32 v[56:57], v[56:57], v[84:85]
	v_pk_mul_f32 v[62:63], v[54:55], v[62:63]
	v_cvt_pk_bf16_f32 v52, v58, v59
	v_cvt_pk_bf16_f32 v53, v60, v61
	v_cvt_pk_bf16_f32 v54, v56, v57
	v_cvt_pk_bf16_f32 v55, v62, v63
	global_store_dwordx4 v[74:75], v[52:55], off sc1
	s_nop 1
	s_branch .Lmg_top
.Lmg_tail:
	s_add_i32 s24, s22, 0x10000
	s_cmp_gt_i32 s24, 0xfffff
	s_cbranch_scc1 .LBB0_450
